# v118 with the G5 ACT stores write-through (sc1) instead of nt
# baseline (speedup 1.0000x reference)
.LBB0_1268:
	s_or_b64 exec, exec, s[56:57]
	v_pk_mul_f32 v[152:153], v[118:119], v[196:197] op_sel_hi:[1,0]
	v_pk_mul_f32 v[118:119], v[122:123], v[192:193] op_sel_hi:[1,0]
	v_pk_mul_f32 v[122:123], v[108:109], v[192:193] op_sel_hi:[1,0]
	v_mov_b32_e32 v108, v188
	v_mov_b32_e32 v109, v188
	v_mov_b32_e32 v189, v188
	v_pk_mul_f32 v[156:157], v[114:115], v[196:197] op_sel_hi:[1,0]
	v_pk_mul_f32 v[114:115], v[126:127], v[192:193] op_sel_hi:[1,0]
	v_pk_mul_f32 v[126:127], v[104:105], v[192:193] op_sel_hi:[1,0]
	v_pk_mul_f32 v[104:105], v[102:103], v[108:109]
	v_pk_mul_f32 v[102:103], v[72:73], v[194:195] op_sel_hi:[1,0]
	v_pk_mul_f32 v[72:73], v[84:85], v[190:191] op_sel_hi:[1,0]
	v_pk_mul_f32 v[84:85], v[58:59], v[190:191] op_sel_hi:[1,0]
	v_pk_mul_f32 v[58:59], v[70:71], v[186:187] op_sel_hi:[1,0]
	v_mov_b32_e32 v70, v150
	v_mov_b32_e32 v71, v151
	v_pk_mul_f32 v[130:131], v[130:131], v[196:197] op_sel_hi:[1,0]
	v_pk_mul_f32 v[158:159], v[112:113], v[196:197] op_sel_hi:[1,0]
	v_pk_mul_f32 v[112:113], v[124:125], v[192:193] op_sel_hi:[1,0]
	v_pk_mul_f32 v[124:125], v[106:107], v[192:193] op_sel_hi:[1,0]
	v_pk_mul_f32 v[106:107], v[100:101], v[188:189]
	v_pk_mul_f32 v[100:101], v[74:75], v[194:195] op_sel_hi:[1,0]
	v_pk_mul_f32 v[74:75], v[86:87], v[190:191] op_sel_hi:[1,0]
	v_pk_mul_f32 v[86:87], v[56:57], v[190:191] op_sel_hi:[1,0]
	v_pk_mul_f32 v[56:57], v[68:69], v[186:187] op_sel_hi:[1,0]
	v_mov_b32_e32 v68, v148
	v_mov_b32_e32 v69, v149
	v_mov_b32_dpp v70, v70 row_ror:1 row_mask:0xf bank_mask:0xf
	v_mov_b32_dpp v71, v71 row_ror:1 row_mask:0xf bank_mask:0xf
	v_pk_mul_f32 v[128:129], v[128:129], v[196:197] op_sel_hi:[1,0]
	v_mov_b32_dpp v68, v68 row_ror:1 row_mask:0xf bank_mask:0xf
	v_mov_b32_dpp v69, v69 row_ror:1 row_mask:0xf bank_mask:0xf
	v_mov_b32_dpp v70, v130 row_shr:1 row_mask:0xf bank_mask:0xf
	v_mov_b32_dpp v150, v150 row_ror:2 row_mask:0xf bank_mask:0xf
	v_mov_b32_dpp v71, v131 row_shr:1 row_mask:0xf bank_mask:0xf
	v_mov_b32_dpp v151, v151 row_ror:2 row_mask:0xf bank_mask:0xf
	v_pk_fma_f32 v[160:161], v[130:131], v[38:39], v[42:43]
	v_mov_b32_dpp v68, v128 row_shr:1 row_mask:0xf bank_mask:0xf
	v_mov_b32_dpp v148, v148 row_ror:2 row_mask:0xf bank_mask:0xf
	v_mov_b32_dpp v69, v129 row_shr:1 row_mask:0xf bank_mask:0xf
	v_mov_b32_dpp v149, v149 row_ror:2 row_mask:0xf bank_mask:0xf
	v_mov_b32_dpp v150, v130 row_shr:2 row_mask:0xf bank_mask:0xf
	v_mov_b32_dpp v151, v131 row_shr:2 row_mask:0xf bank_mask:0xf
	v_pk_fma_f32 v[162:163], v[128:129], v[36:37], v[40:41]
	v_pk_fma_f32 v[70:71], v[34:35], v[70:71], v[160:161]
	v_mov_b32_dpp v148, v128 row_shr:2 row_mask:0xf bank_mask:0xf
	v_mov_b32_dpp v149, v129 row_shr:2 row_mask:0xf bank_mask:0xf
	v_pk_fma_f32 v[68:69], v[32:33], v[68:69], v[162:163]
	v_pk_fma_f32 v[70:71], v[30:31], v[150:151], v[70:71]
	v_pk_mul_f32 v[154:155], v[116:117], v[196:197] op_sel_hi:[1,0]
	v_pk_mul_f32 v[116:117], v[120:121], v[192:193] op_sel_hi:[1,0]
	v_pk_mul_f32 v[120:121], v[110:111], v[192:193] op_sel_hi:[1,0]
	v_pk_mul_f32 v[108:109], v[98:99], v[108:109]
	v_pk_mul_f32 v[110:111], v[96:97], v[188:189]
	v_pk_mul_f32 v[96:97], v[78:79], v[194:195] op_sel_hi:[1,0]
	v_pk_mul_f32 v[98:99], v[76:77], v[194:195] op_sel_hi:[1,0]
	v_pk_mul_f32 v[78:79], v[82:83], v[190:191] op_sel_hi:[1,0]
	v_pk_mul_f32 v[76:77], v[80:81], v[190:191] op_sel_hi:[1,0]
	v_pk_mul_f32 v[80:81], v[62:63], v[190:191] op_sel_hi:[1,0]
	v_pk_mul_f32 v[82:83], v[60:61], v[190:191] op_sel_hi:[1,0]
	v_pk_mul_f32 v[62:63], v[66:67], v[186:187] op_sel_hi:[1,0]
	v_pk_mul_f32 v[60:61], v[64:65], v[186:187] op_sel_hi:[1,0]
	v_mov_b32_e32 v64, v182
	v_mov_b32_e32 v65, v182
	v_mov_b32_e32 v66, v146
	v_mov_b32_e32 v67, v147
	v_pk_fma_f32 v[68:69], v[28:29], v[148:149], v[68:69]
	v_pk_mul_f32 v[148:149], v[70:71], v[70:71]
	v_pk_mul_f32 v[134:135], v[134:135], v[196:197] op_sel_hi:[1,0]
	v_pk_mul_f32 v[46:47], v[46:47], v[64:65]
	v_pk_mul_f32 v[2:3], v[2:3], v[64:65]
	v_mov_b32_e32 v64, v144
	v_mov_b32_e32 v65, v145
	v_mov_b32_dpp v66, v66 row_ror:1 row_mask:0xf bank_mask:0xf
	v_mov_b32_dpp v67, v67 row_ror:1 row_mask:0xf bank_mask:0xf
	v_pk_mul_f32 v[150:151], v[68:69], v[68:69]
	v_pk_fma_f32 v[148:149], v[148:149], s[30:31], 1.0 op_sel_hi:[1,0,0]
	v_pk_mul_f32 v[132:133], v[132:133], v[196:197] op_sel_hi:[1,0]
	v_mov_b32_dpp v64, v64 row_ror:1 row_mask:0xf bank_mask:0xf
	v_mov_b32_dpp v65, v65 row_ror:1 row_mask:0xf bank_mask:0xf
	v_mov_b32_dpp v66, v134 row_shr:1 row_mask:0xf bank_mask:0xf
	v_mov_b32_dpp v146, v146 row_ror:2 row_mask:0xf bank_mask:0xf
	v_mov_b32_dpp v67, v135 row_shr:1 row_mask:0xf bank_mask:0xf
	v_mov_b32_dpp v147, v147 row_ror:2 row_mask:0xf bank_mask:0xf
	v_pk_fma_f32 v[150:151], v[150:151], s[30:31], 1.0 op_sel_hi:[1,0,0]
	v_pk_mul_f32 v[148:149], v[70:71], v[148:149]
	v_pk_mul_f32 v[70:71], v[156:157], v[70:71]
	v_pk_fma_f32 v[156:157], v[134:135], v[22:23], v[26:27]
	v_mov_b32_dpp v64, v132 row_shr:1 row_mask:0xf bank_mask:0xf
	v_mov_b32_dpp v144, v144 row_ror:2 row_mask:0xf bank_mask:0xf
	v_mov_b32_dpp v65, v133 row_shr:1 row_mask:0xf bank_mask:0xf
	v_mov_b32_dpp v145, v145 row_ror:2 row_mask:0xf bank_mask:0xf
	v_mov_b32_dpp v146, v134 row_shr:2 row_mask:0xf bank_mask:0xf
	v_mov_b32_dpp v147, v135 row_shr:2 row_mask:0xf bank_mask:0xf
	v_pk_mul_f32 v[150:151], v[68:69], v[150:151]
	v_pk_mul_f32 v[68:69], v[158:159], v[68:69]
	v_pk_fma_f32 v[158:159], v[132:133], v[20:21], v[24:25]
	v_pk_fma_f32 v[66:67], v[18:19], v[66:67], v[156:157]
	v_mov_b32_dpp v144, v132 row_shr:2 row_mask:0xf bank_mask:0xf
	v_mov_b32_dpp v145, v133 row_shr:2 row_mask:0xf bank_mask:0xf
	v_pk_fma_f32 v[64:65], v[16:17], v[64:65], v[158:159]
	v_pk_fma_f32 v[66:67], v[14:15], v[146:147], v[66:67]
	v_pk_fma_f32 v[64:65], v[12:13], v[144:145], v[64:65]
	v_pk_mul_f32 v[144:145], v[66:67], v[66:67]
	v_pk_mul_f32 v[146:147], v[64:65], v[64:65]
	v_pk_fma_f32 v[144:145], v[144:145], s[30:31], 1.0 op_sel_hi:[1,0,0]
	v_pk_fma_f32 v[146:147], v[146:147], s[30:31], 1.0 op_sel_hi:[1,0,0]
	v_pk_mul_f32 v[144:145], v[66:67], v[144:145]
	v_pk_mul_f32 v[148:149], v[148:149], s[34:35] op_sel_hi:[1,0]
	v_pk_mul_f32 v[150:151], v[150:151], s[34:35] op_sel_hi:[1,0]
	v_pk_mul_f32 v[146:147], v[64:65], v[146:147]
	v_pk_mul_f32 v[144:145], v[144:145], s[34:35] op_sel_hi:[1,0]
	v_exp_f32_e32 v150, v150
	v_exp_f32_e32 v148, v148
	v_exp_f32_e32 v149, v149
	v_exp_f32_e32 v151, v151
	v_pk_mul_f32 v[146:147], v[146:147], s[34:35] op_sel_hi:[1,0]
	v_exp_f32_e32 v144, v144
	v_exp_f32_e32 v145, v145
	v_exp_f32_e32 v146, v146
	v_exp_f32_e32 v147, v147
	v_pk_add_f32 v[148:149], v[148:149], 1.0 op_sel_hi:[1,0]
	v_pk_add_f32 v[150:151], v[150:151], 1.0 op_sel_hi:[1,0]
	v_pk_add_f32 v[144:145], v[144:145], 1.0 op_sel_hi:[1,0]
	v_rcp_f32_e32 v150, v150
	v_rcp_f32_e32 v151, v151
	v_rcp_f32_e32 v148, v148
	v_rcp_f32_e32 v149, v149
	v_pk_add_f32 v[146:147], v[146:147], 1.0 op_sel_hi:[1,0]
	v_rcp_f32_e32 v144, v144
	v_rcp_f32_e32 v145, v145
	v_rcp_f32_e32 v146, v146
	v_rcp_f32_e32 v147, v147
	v_pk_mul_f32 v[66:67], v[152:153], v[66:67]
	v_pk_mul_f32 v[70:71], v[70:71], v[148:149]
	v_pk_mul_f32 v[68:69], v[68:69], v[150:151]
	v_pk_mul_f32 v[64:65], v[154:155], v[64:65]
	v_pk_mul_f32 v[144:145], v[66:67], v[144:145]
	v_pk_mul_f32 v[64:65], v[64:65], v[146:147]
	v_pk_fma_f32 v[146:147], v[118:119], v[38:39], v[42:43]
	v_cvt_pk_bf16_f32 v66, v64, v65
	v_cvt_pk_bf16_f32 v67, v144, v145
	v_cvt_pk_bf16_f32 v68, v68, v69
	v_cvt_pk_bf16_f32 v69, v70, v71
	v_mov_b32_e32 v70, v128
	v_mov_b32_e32 v71, v129
	v_mov_b32_e32 v144, v130
	v_mov_b32_e32 v145, v131
	v_mov_b32_dpp v70, v70 row_ror:1 row_mask:0xf bank_mask:0xf
	v_mov_b32_dpp v71, v71 row_ror:1 row_mask:0xf bank_mask:0xf
	v_mov_b32_dpp v144, v144 row_ror:1 row_mask:0xf bank_mask:0xf
	v_mov_b32_dpp v145, v145 row_ror:1 row_mask:0xf bank_mask:0xf
	v_mov_b32_dpp v70, v116 row_shr:1 row_mask:0xf bank_mask:0xf
	v_mov_b32_dpp v128, v128 row_ror:2 row_mask:0xf bank_mask:0xf
	v_mov_b32_dpp v71, v117 row_shr:1 row_mask:0xf bank_mask:0xf
	v_mov_b32_dpp v129, v129 row_ror:2 row_mask:0xf bank_mask:0xf
	v_mov_b32_dpp v144, v118 row_shr:1 row_mask:0xf bank_mask:0xf
	v_mov_b32_dpp v130, v130 row_ror:2 row_mask:0xf bank_mask:0xf
	v_mov_b32_dpp v145, v119 row_shr:1 row_mask:0xf bank_mask:0xf
	v_mov_b32_dpp v131, v131 row_ror:2 row_mask:0xf bank_mask:0xf
	v_pk_fma_f32 v[148:149], v[116:117], v[36:37], v[40:41]
	v_mov_b32_dpp v128, v116 row_shr:2 row_mask:0xf bank_mask:0xf
	v_mov_b32_dpp v129, v117 row_shr:2 row_mask:0xf bank_mask:0xf
	v_mov_b32_dpp v130, v118 row_shr:2 row_mask:0xf bank_mask:0xf
	v_mov_b32_dpp v131, v119 row_shr:2 row_mask:0xf bank_mask:0xf
	v_pk_fma_f32 v[144:145], v[34:35], v[144:145], v[146:147]
	v_pk_fma_f32 v[70:71], v[32:33], v[70:71], v[148:149]
	v_pk_fma_f32 v[130:131], v[30:31], v[130:131], v[144:145]
	v_pk_fma_f32 v[70:71], v[28:29], v[128:129], v[70:71]
	v_pk_mul_f32 v[128:129], v[130:131], v[130:131]
	v_pk_mul_f32 v[144:145], v[70:71], v[70:71]
	v_pk_fma_f32 v[128:129], v[128:129], s[30:31], 1.0 op_sel_hi:[1,0,0]
	v_pk_fma_f32 v[144:145], v[144:145], s[30:31], 1.0 op_sel_hi:[1,0,0]
	v_pk_mul_f32 v[128:129], v[130:131], v[128:129]
	v_pk_mul_f32 v[144:145], v[70:71], v[144:145]
	v_pk_mul_f32 v[128:129], v[128:129], s[34:35] op_sel_hi:[1,0]
	v_pk_mul_f32 v[144:145], v[144:145], s[34:35] op_sel_hi:[1,0]
	v_add_lshl_u32 v64, v210, v184, 1
	v_exp_f32_e32 v144, v144
	v_exp_f32_e32 v128, v128
	v_exp_f32_e32 v129, v129
	v_exp_f32_e32 v145, v145
	v_add_u32_e32 v65, 0x16000, v64
	global_store_dwordx4 v65, v[66:69], s[18:19] sc1
	v_pk_mul_f32 v[124:125], v[124:125], v[130:131]
	v_pk_mul_f32 v[70:71], v[126:127], v[70:71]
	v_mov_b32_e32 v66, v132
	v_mov_b32_e32 v67, v133
	v_mov_b32_e32 v68, v134
	v_mov_b32_e32 v69, v135
	v_mov_b32_dpp v66, v66 row_ror:1 row_mask:0xf bank_mask:0xf
	v_mov_b32_dpp v67, v67 row_ror:1 row_mask:0xf bank_mask:0xf
	v_mov_b32_dpp v68, v68 row_ror:1 row_mask:0xf bank_mask:0xf
	v_mov_b32_dpp v69, v69 row_ror:1 row_mask:0xf bank_mask:0xf
	v_mov_b32_dpp v66, v112 row_shr:1 row_mask:0xf bank_mask:0xf
	v_mov_b32_dpp v132, v132 row_ror:2 row_mask:0xf bank_mask:0xf
	v_mov_b32_dpp v67, v113 row_shr:1 row_mask:0xf bank_mask:0xf
	v_mov_b32_dpp v133, v133 row_ror:2 row_mask:0xf bank_mask:0xf
	v_mov_b32_dpp v68, v114 row_shr:1 row_mask:0xf bank_mask:0xf
	v_mov_b32_dpp v134, v134 row_ror:2 row_mask:0xf bank_mask:0xf
	v_mov_b32_dpp v69, v115 row_shr:1 row_mask:0xf bank_mask:0xf
	v_mov_b32_dpp v135, v135 row_ror:2 row_mask:0xf bank_mask:0xf
	v_pk_add_f32 v[126:127], v[128:129], 1.0 op_sel_hi:[1,0]
	v_pk_add_f32 v[128:129], v[144:145], 1.0 op_sel_hi:[1,0]
	v_pk_fma_f32 v[130:131], v[114:115], v[22:23], v[26:27]
	v_pk_fma_f32 v[144:145], v[112:113], v[20:21], v[24:25]
	v_mov_b32_dpp v132, v112 row_shr:2 row_mask:0xf bank_mask:0xf
	v_mov_b32_dpp v133, v113 row_shr:2 row_mask:0xf bank_mask:0xf
	v_mov_b32_dpp v134, v114 row_shr:2 row_mask:0xf bank_mask:0xf
	v_mov_b32_dpp v135, v115 row_shr:2 row_mask:0xf bank_mask:0xf
	v_pk_fma_f32 v[68:69], v[18:19], v[68:69], v[130:131]
	v_pk_fma_f32 v[66:67], v[16:17], v[66:67], v[144:145]
	v_pk_fma_f32 v[68:69], v[14:15], v[134:135], v[68:69]
	v_pk_fma_f32 v[66:67], v[12:13], v[132:133], v[66:67]
	v_pk_mul_f32 v[130:131], v[68:69], v[68:69]
	v_pk_mul_f32 v[132:133], v[66:67], v[66:67]
	v_pk_fma_f32 v[130:131], v[130:131], s[30:31], 1.0 op_sel_hi:[1,0,0]
	v_pk_fma_f32 v[132:133], v[132:133], s[30:31], 1.0 op_sel_hi:[1,0,0]
	v_pk_mul_f32 v[130:131], v[68:69], v[130:131]
	v_pk_mul_f32 v[132:133], v[66:67], v[132:133]
	v_pk_mul_f32 v[130:131], v[130:131], s[34:35] op_sel_hi:[1,0]
	v_pk_mul_f32 v[132:133], v[132:133], s[34:35] op_sel_hi:[1,0]
	v_rcp_f32_e32 v128, v128
	v_rcp_f32_e32 v129, v129
	v_rcp_f32_e32 v126, v126
	v_rcp_f32_e32 v127, v127
	v_exp_f32_e32 v132, v132
	v_exp_f32_e32 v130, v130
	v_exp_f32_e32 v131, v131
	v_exp_f32_e32 v133, v133
	v_pk_mul_f32 v[124:125], v[124:125], v[126:127]
	v_pk_mul_f32 v[70:71], v[70:71], v[128:129]
	v_pk_add_f32 v[126:127], v[130:131], 1.0 op_sel_hi:[1,0]
	v_pk_add_f32 v[128:129], v[132:133], 1.0 op_sel_hi:[1,0]
	v_rcp_f32_e32 v126, v126
	v_rcp_f32_e32 v128, v128
	v_rcp_f32_e32 v127, v127
	v_rcp_f32_e32 v129, v129
	v_pk_mul_f32 v[68:69], v[120:121], v[68:69]
	v_pk_mul_f32 v[66:67], v[122:123], v[66:67]
	v_pk_mul_f32 v[68:69], v[68:69], v[126:127]
	v_pk_mul_f32 v[66:67], v[66:67], v[128:129]
	v_mov_b32_e32 v120, v118
	v_cvt_pk_bf16_f32 v66, v66, v67
	v_cvt_pk_bf16_f32 v67, v68, v69
	v_cvt_pk_bf16_f32 v68, v70, v71
	v_mov_b32_e32 v70, v116
	v_mov_b32_e32 v71, v117
	v_mov_b32_e32 v121, v119
	v_mov_b32_dpp v70, v70 row_ror:1 row_mask:0xf bank_mask:0xf
	v_mov_b32_dpp v71, v71 row_ror:1 row_mask:0xf bank_mask:0xf
	v_mov_b32_dpp v120, v120 row_ror:1 row_mask:0xf bank_mask:0xf
	v_mov_b32_dpp v121, v121 row_ror:1 row_mask:0xf bank_mask:0xf
	v_cvt_pk_bf16_f32 v69, v124, v125
	v_mov_b32_dpp v70, v140 row_shr:1 row_mask:0xf bank_mask:0xf
	v_mov_b32_dpp v116, v116 row_ror:2 row_mask:0xf bank_mask:0xf
	v_mov_b32_dpp v71, v141 row_shr:1 row_mask:0xf bank_mask:0xf
	v_mov_b32_dpp v117, v117 row_ror:2 row_mask:0xf bank_mask:0xf
	v_mov_b32_dpp v120, v142 row_shr:1 row_mask:0xf bank_mask:0xf
	v_mov_b32_dpp v118, v118 row_ror:2 row_mask:0xf bank_mask:0xf
	v_mov_b32_dpp v121, v143 row_shr:1 row_mask:0xf bank_mask:0xf
	v_mov_b32_dpp v119, v119 row_ror:2 row_mask:0xf bank_mask:0xf
	v_pk_fma_f32 v[122:123], v[142:143], v[38:39], v[42:43]
	v_pk_fma_f32 v[124:125], v[140:141], v[36:37], v[40:41]
	v_mov_b32_dpp v116, v140 row_shr:2 row_mask:0xf bank_mask:0xf
	v_mov_b32_dpp v117, v141 row_shr:2 row_mask:0xf bank_mask:0xf
	v_mov_b32_dpp v118, v142 row_shr:2 row_mask:0xf bank_mask:0xf
	v_mov_b32_dpp v119, v143 row_shr:2 row_mask:0xf bank_mask:0xf
	v_pk_fma_f32 v[120:121], v[34:35], v[120:121], v[122:123]
	v_pk_fma_f32 v[70:71], v[32:33], v[70:71], v[124:125]
	v_pk_fma_f32 v[118:119], v[30:31], v[118:119], v[120:121]
	v_pk_fma_f32 v[70:71], v[28:29], v[116:117], v[70:71]
	v_pk_mul_f32 v[116:117], v[118:119], v[118:119]
	v_pk_mul_f32 v[120:121], v[70:71], v[70:71]
	v_pk_fma_f32 v[116:117], v[116:117], s[30:31], 1.0 op_sel_hi:[1,0,0]
	v_pk_fma_f32 v[120:121], v[120:121], s[30:31], 1.0 op_sel_hi:[1,0,0]
	v_pk_mul_f32 v[116:117], v[118:119], v[116:117]
	v_pk_mul_f32 v[120:121], v[70:71], v[120:121]
	v_pk_mul_f32 v[116:117], v[116:117], s[34:35] op_sel_hi:[1,0]
	v_pk_mul_f32 v[120:121], v[120:121], s[34:35] op_sel_hi:[1,0]
	v_exp_f32_e32 v116, v116
	v_exp_f32_e32 v120, v120
	v_exp_f32_e32 v117, v117
	v_exp_f32_e32 v121, v121
	v_add_u32_e32 v65, 0x2c000, v64
	global_store_dwordx4 v65, v[66:69], s[18:19] sc1
	v_pk_mul_f32 v[108:109], v[108:109], v[118:119]
	v_pk_mul_f32 v[70:71], v[110:111], v[70:71]
	v_mov_b32_e32 v66, v112
	v_mov_b32_e32 v67, v113
	v_mov_b32_e32 v68, v114
	v_mov_b32_e32 v69, v115
	v_mov_b32_dpp v66, v66 row_ror:1 row_mask:0xf bank_mask:0xf
	v_mov_b32_dpp v67, v67 row_ror:1 row_mask:0xf bank_mask:0xf
	v_mov_b32_dpp v68, v68 row_ror:1 row_mask:0xf bank_mask:0xf
	v_mov_b32_dpp v69, v69 row_ror:1 row_mask:0xf bank_mask:0xf
	v_mov_b32_dpp v66, v136 row_shr:1 row_mask:0xf bank_mask:0xf
	v_mov_b32_dpp v112, v112 row_ror:2 row_mask:0xf bank_mask:0xf
	v_mov_b32_dpp v67, v137 row_shr:1 row_mask:0xf bank_mask:0xf
	v_mov_b32_dpp v113, v113 row_ror:2 row_mask:0xf bank_mask:0xf
	v_mov_b32_dpp v68, v138 row_shr:1 row_mask:0xf bank_mask:0xf
	v_mov_b32_dpp v114, v114 row_ror:2 row_mask:0xf bank_mask:0xf
	v_mov_b32_dpp v69, v139 row_shr:1 row_mask:0xf bank_mask:0xf
	v_mov_b32_dpp v115, v115 row_ror:2 row_mask:0xf bank_mask:0xf
	v_pk_add_f32 v[110:111], v[116:117], 1.0 op_sel_hi:[1,0]
	v_pk_add_f32 v[116:117], v[120:121], 1.0 op_sel_hi:[1,0]
	v_pk_fma_f32 v[118:119], v[138:139], v[22:23], v[26:27]
	v_pk_fma_f32 v[120:121], v[136:137], v[20:21], v[24:25]
	v_mov_b32_dpp v112, v136 row_shr:2 row_mask:0xf bank_mask:0xf
	v_mov_b32_dpp v113, v137 row_shr:2 row_mask:0xf bank_mask:0xf
	v_mov_b32_dpp v114, v138 row_shr:2 row_mask:0xf bank_mask:0xf
	v_mov_b32_dpp v115, v139 row_shr:2 row_mask:0xf bank_mask:0xf
	v_pk_fma_f32 v[68:69], v[18:19], v[68:69], v[118:119]
	v_pk_fma_f32 v[66:67], v[16:17], v[66:67], v[120:121]
	v_pk_fma_f32 v[68:69], v[14:15], v[114:115], v[68:69]
	v_pk_fma_f32 v[66:67], v[12:13], v[112:113], v[66:67]
	v_pk_mul_f32 v[112:113], v[68:69], v[68:69]
	v_pk_mul_f32 v[114:115], v[66:67], v[66:67]
	v_pk_fma_f32 v[112:113], v[112:113], s[30:31], 1.0 op_sel_hi:[1,0,0]
	v_pk_fma_f32 v[114:115], v[114:115], s[30:31], 1.0 op_sel_hi:[1,0,0]
	v_pk_mul_f32 v[112:113], v[68:69], v[112:113]
	v_pk_mul_f32 v[114:115], v[66:67], v[114:115]
	v_pk_mul_f32 v[112:113], v[112:113], s[34:35] op_sel_hi:[1,0]
	v_pk_mul_f32 v[114:115], v[114:115], s[34:35] op_sel_hi:[1,0]
	v_rcp_f32_e32 v110, v110
	v_rcp_f32_e32 v111, v111
	v_exp_f32_e32 v114, v114
	v_exp_f32_e32 v112, v112
	v_exp_f32_e32 v113, v113
	v_exp_f32_e32 v115, v115
	v_pk_mul_f32 v[108:109], v[108:109], v[110:111]
	v_rcp_f32_e32 v116, v116
	v_pk_add_f32 v[110:111], v[112:113], 1.0 op_sel_hi:[1,0]
	v_pk_add_f32 v[112:113], v[114:115], 1.0 op_sel_hi:[1,0]
	v_rcp_f32_e32 v117, v117
	v_rcp_f32_e32 v112, v112
	v_rcp_f32_e32 v110, v110
	v_rcp_f32_e32 v111, v111
	v_rcp_f32_e32 v113, v113
	v_pk_mul_f32 v[68:69], v[104:105], v[68:69]
	v_pk_mul_f32 v[66:67], v[106:107], v[66:67]
	v_pk_mul_f32 v[70:71], v[70:71], v[116:117]
	v_pk_mul_f32 v[68:69], v[68:69], v[110:111]
	v_pk_mul_f32 v[66:67], v[66:67], v[112:113]
	v_add3_u32 v65, s73, v176, v209
	v_cvt_pk_bf16_f32 v66, v66, v67
	v_cvt_pk_bf16_f32 v67, v68, v69
	v_cvt_pk_bf16_f32 v68, v70, v71
	v_cvt_pk_bf16_f32 v69, v108, v109
	v_add_u32_e32 v70, 0x42000, v64
	ds_read_b128 v[104:107], v65 offset:2048
	global_store_dwordx4 v70, v[66:69], s[18:19] sc1
	ds_read_b128 v[66:69], v65 offset:2064
	v_pk_mul_f32 v[90:91], v[90:91], v[194:195] op_sel_hi:[1,0]
	v_pk_mul_f32 v[88:89], v[88:89], v[194:195] op_sel_hi:[1,0]
	v_pk_fma_f32 v[114:115], v[90:91], v[38:39], v[42:43]
	v_pk_fma_f32 v[116:117], v[88:89], v[36:37], v[40:41]
	s_waitcnt lgkmcnt(0)
	v_mov_b32_e32 v110, v66
	v_mov_b32_e32 v111, v67
	v_mov_b32_e32 v112, v68
	v_mov_b32_e32 v113, v69
	v_mov_b32_dpp v110, v110 row_ror:1 row_mask:0xf bank_mask:0xf
	v_mov_b32_dpp v111, v111 row_ror:1 row_mask:0xf bank_mask:0xf
	v_mov_b32_dpp v112, v112 row_ror:1 row_mask:0xf bank_mask:0xf
	v_mov_b32_dpp v113, v113 row_ror:1 row_mask:0xf bank_mask:0xf
	v_mov_b32_dpp v110, v88 row_shr:1 row_mask:0xf bank_mask:0xf
	v_mov_b32_dpp v66, v66 row_ror:2 row_mask:0xf bank_mask:0xf
	v_mov_b32_dpp v111, v89 row_shr:1 row_mask:0xf bank_mask:0xf
	v_mov_b32_dpp v67, v67 row_ror:2 row_mask:0xf bank_mask:0xf
	v_mov_b32_dpp v112, v90 row_shr:1 row_mask:0xf bank_mask:0xf
	v_mov_b32_dpp v68, v68 row_ror:2 row_mask:0xf bank_mask:0xf
	v_mov_b32_dpp v113, v91 row_shr:1 row_mask:0xf bank_mask:0xf
	v_mov_b32_dpp v69, v69 row_ror:2 row_mask:0xf bank_mask:0xf
	v_mov_b32_dpp v66, v88 row_shr:2 row_mask:0xf bank_mask:0xf
	v_mov_b32_dpp v67, v89 row_shr:2 row_mask:0xf bank_mask:0xf
	v_mov_b32_dpp v68, v90 row_shr:2 row_mask:0xf bank_mask:0xf
	v_mov_b32_dpp v69, v91 row_shr:2 row_mask:0xf bank_mask:0xf
	v_pk_fma_f32 v[112:113], v[34:35], v[112:113], v[114:115]
	v_pk_fma_f32 v[110:111], v[32:33], v[110:111], v[116:117]
	v_pk_fma_f32 v[68:69], v[30:31], v[68:69], v[112:113]
	v_pk_fma_f32 v[66:67], v[28:29], v[66:67], v[110:111]
	v_pk_mul_f32 v[112:113], v[68:69], v[68:69]
	v_pk_mul_f32 v[110:111], v[66:67], v[66:67]
	v_pk_fma_f32 v[112:113], v[112:113], s[30:31], 1.0 op_sel_hi:[1,0,0]
	v_pk_fma_f32 v[110:111], v[110:111], s[30:31], 1.0 op_sel_hi:[1,0,0]
	v_pk_mul_f32 v[112:113], v[68:69], v[112:113]
	v_pk_mul_f32 v[110:111], v[66:67], v[110:111]
	v_pk_mul_f32 v[112:113], v[112:113], s[34:35] op_sel_hi:[1,0]
	v_pk_mul_f32 v[110:111], v[110:111], s[34:35] op_sel_hi:[1,0]
	v_exp_f32_e32 v112, v112
	v_exp_f32_e32 v110, v110
	v_exp_f32_e32 v113, v113
	v_exp_f32_e32 v111, v111
	v_mov_b32_e32 v70, v104
	v_mov_b32_e32 v71, v105
	v_mov_b32_e32 v108, v106
	v_mov_b32_e32 v109, v107
	v_pk_mul_f32 v[94:95], v[94:95], v[194:195] op_sel_hi:[1,0]
	v_pk_mul_f32 v[92:93], v[92:93], v[194:195] op_sel_hi:[1,0]
	v_mov_b32_dpp v70, v70 row_ror:1 row_mask:0xf bank_mask:0xf
	v_mov_b32_dpp v71, v71 row_ror:1 row_mask:0xf bank_mask:0xf
	v_mov_b32_dpp v108, v108 row_ror:1 row_mask:0xf bank_mask:0xf
	v_mov_b32_dpp v109, v109 row_ror:1 row_mask:0xf bank_mask:0xf
	v_mov_b32_dpp v70, v92 row_shr:1 row_mask:0xf bank_mask:0xf
	v_mov_b32_dpp v104, v104 row_ror:2 row_mask:0xf bank_mask:0xf
	v_mov_b32_dpp v71, v93 row_shr:1 row_mask:0xf bank_mask:0xf
	v_mov_b32_dpp v105, v105 row_ror:2 row_mask:0xf bank_mask:0xf
	v_mov_b32_dpp v108, v94 row_shr:1 row_mask:0xf bank_mask:0xf
	v_mov_b32_dpp v106, v106 row_ror:2 row_mask:0xf bank_mask:0xf
	v_mov_b32_dpp v109, v95 row_shr:1 row_mask:0xf bank_mask:0xf
	v_mov_b32_dpp v107, v107 row_ror:2 row_mask:0xf bank_mask:0xf
	v_pk_mul_f32 v[68:69], v[100:101], v[68:69]
	v_pk_mul_f32 v[66:67], v[102:103], v[66:67]
	v_pk_add_f32 v[100:101], v[112:113], 1.0 op_sel_hi:[1,0]
	v_pk_add_f32 v[102:103], v[110:111], 1.0 op_sel_hi:[1,0]
	v_pk_fma_f32 v[110:111], v[94:95], v[22:23], v[26:27]
	v_pk_fma_f32 v[112:113], v[92:93], v[20:21], v[24:25]
	v_mov_b32_dpp v104, v92 row_shr:2 row_mask:0xf bank_mask:0xf
	v_mov_b32_dpp v105, v93 row_shr:2 row_mask:0xf bank_mask:0xf
	v_mov_b32_dpp v106, v94 row_shr:2 row_mask:0xf bank_mask:0xf
	v_mov_b32_dpp v107, v95 row_shr:2 row_mask:0xf bank_mask:0xf
	v_pk_fma_f32 v[108:109], v[18:19], v[108:109], v[110:111]
	v_pk_fma_f32 v[70:71], v[16:17], v[70:71], v[112:113]
	v_rcp_f32_e32 v102, v102
	v_pk_fma_f32 v[70:71], v[12:13], v[104:105], v[70:71]
	v_pk_fma_f32 v[104:105], v[14:15], v[106:107], v[108:109]
	v_pk_mul_f32 v[106:107], v[70:71], v[70:71]
	v_pk_mul_f32 v[108:109], v[104:105], v[104:105]
	v_pk_fma_f32 v[106:107], v[106:107], s[30:31], 1.0 op_sel_hi:[1,0,0]
	v_pk_fma_f32 v[108:109], v[108:109], s[30:31], 1.0 op_sel_hi:[1,0,0]
	v_pk_mul_f32 v[106:107], v[70:71], v[106:107]
	v_pk_mul_f32 v[108:109], v[104:105], v[108:109]
	v_pk_mul_f32 v[106:107], v[106:107], s[34:35] op_sel_hi:[1,0]
	v_pk_mul_f32 v[108:109], v[108:109], s[34:35] op_sel_hi:[1,0]
	v_rcp_f32_e32 v103, v103
	v_rcp_f32_e32 v100, v100
	v_rcp_f32_e32 v101, v101
	v_exp_f32_e32 v106, v106
	v_exp_f32_e32 v108, v108
	v_exp_f32_e32 v109, v109
	v_exp_f32_e32 v107, v107
	v_pk_mul_f32 v[102:103], v[66:67], v[102:103]
	v_pk_mul_f32 v[100:101], v[68:69], v[100:101]
	v_pk_add_f32 v[66:67], v[108:109], 1.0 op_sel_hi:[1,0]
	v_pk_add_f32 v[68:69], v[106:107], 1.0 op_sel_hi:[1,0]
	v_rcp_f32_e32 v66, v66
	v_rcp_f32_e32 v68, v68
	v_rcp_f32_e32 v69, v69
	v_rcp_f32_e32 v67, v67
	v_pk_mul_f32 v[96:97], v[96:97], v[104:105]
	v_pk_mul_f32 v[70:71], v[98:99], v[70:71]
	v_pk_fma_f32 v[98:99], v[78:79], v[38:39], v[42:43]
	v_pk_mul_f32 v[68:69], v[70:71], v[68:69]
	v_pk_mul_f32 v[70:71], v[96:97], v[66:67]
	v_cvt_pk_bf16_f32 v66, v68, v69
	v_mov_b32_e32 v96, v90
	v_cvt_pk_bf16_f32 v67, v70, v71
	v_mov_b32_e32 v70, v88
	v_mov_b32_e32 v71, v89
	v_mov_b32_e32 v97, v91
	v_mov_b32_dpp v70, v70 row_ror:1 row_mask:0xf bank_mask:0xf
	v_mov_b32_dpp v71, v71 row_ror:1 row_mask:0xf bank_mask:0xf
	v_mov_b32_dpp v96, v96 row_ror:1 row_mask:0xf bank_mask:0xf
	v_mov_b32_dpp v97, v97 row_ror:1 row_mask:0xf bank_mask:0xf
	v_cvt_pk_bf16_f32 v68, v102, v103
	v_cvt_pk_bf16_f32 v69, v100, v101
	v_mov_b32_dpp v70, v76 row_shr:1 row_mask:0xf bank_mask:0xf
	v_mov_b32_dpp v88, v88 row_ror:2 row_mask:0xf bank_mask:0xf
	v_mov_b32_dpp v71, v77 row_shr:1 row_mask:0xf bank_mask:0xf
	v_mov_b32_dpp v89, v89 row_ror:2 row_mask:0xf bank_mask:0xf
	v_mov_b32_dpp v96, v78 row_shr:1 row_mask:0xf bank_mask:0xf
	v_mov_b32_dpp v90, v90 row_ror:2 row_mask:0xf bank_mask:0xf
	v_mov_b32_dpp v97, v79 row_shr:1 row_mask:0xf bank_mask:0xf
	v_mov_b32_dpp v91, v91 row_ror:2 row_mask:0xf bank_mask:0xf
	v_pk_fma_f32 v[100:101], v[76:77], v[36:37], v[40:41]
	v_mov_b32_dpp v88, v76 row_shr:2 row_mask:0xf bank_mask:0xf
	v_mov_b32_dpp v89, v77 row_shr:2 row_mask:0xf bank_mask:0xf
	v_mov_b32_dpp v90, v78 row_shr:2 row_mask:0xf bank_mask:0xf
	v_mov_b32_dpp v91, v79 row_shr:2 row_mask:0xf bank_mask:0xf
	v_pk_fma_f32 v[96:97], v[34:35], v[96:97], v[98:99]
	v_pk_fma_f32 v[70:71], v[32:33], v[70:71], v[100:101]
	v_pk_fma_f32 v[90:91], v[30:31], v[90:91], v[96:97]
	v_pk_fma_f32 v[70:71], v[28:29], v[88:89], v[70:71]
	v_pk_mul_f32 v[88:89], v[90:91], v[90:91]
	v_pk_mul_f32 v[96:97], v[70:71], v[70:71]
	v_pk_fma_f32 v[88:89], v[88:89], s[30:31], 1.0 op_sel_hi:[1,0,0]
	v_pk_fma_f32 v[96:97], v[96:97], s[30:31], 1.0 op_sel_hi:[1,0,0]
	v_pk_mul_f32 v[88:89], v[90:91], v[88:89]
	v_pk_mul_f32 v[96:97], v[70:71], v[96:97]
	v_pk_mul_f32 v[88:89], v[88:89], s[34:35] op_sel_hi:[1,0]
	v_pk_mul_f32 v[96:97], v[96:97], s[34:35] op_sel_hi:[1,0]
	v_exp_f32_e32 v88, v88
	v_exp_f32_e32 v96, v96
	v_exp_f32_e32 v89, v89
	v_exp_f32_e32 v97, v97
	v_add_u32_e32 v65, 0xb0000, v64
	global_store_dwordx4 v65, v[66:69], s[18:19] sc1
	v_pk_mul_f32 v[84:85], v[84:85], v[90:91]
	v_pk_mul_f32 v[70:71], v[86:87], v[70:71]
	v_mov_b32_e32 v66, v92
	v_mov_b32_e32 v67, v93
	v_mov_b32_e32 v68, v94
	v_mov_b32_e32 v69, v95
	v_mov_b32_dpp v66, v66 row_ror:1 row_mask:0xf bank_mask:0xf
	v_mov_b32_dpp v67, v67 row_ror:1 row_mask:0xf bank_mask:0xf
	v_mov_b32_dpp v68, v68 row_ror:1 row_mask:0xf bank_mask:0xf
	v_mov_b32_dpp v69, v69 row_ror:1 row_mask:0xf bank_mask:0xf
	v_mov_b32_dpp v66, v72 row_shr:1 row_mask:0xf bank_mask:0xf
	v_mov_b32_dpp v92, v92 row_ror:2 row_mask:0xf bank_mask:0xf
	v_mov_b32_dpp v67, v73 row_shr:1 row_mask:0xf bank_mask:0xf
	v_mov_b32_dpp v93, v93 row_ror:2 row_mask:0xf bank_mask:0xf
	v_mov_b32_dpp v68, v74 row_shr:1 row_mask:0xf bank_mask:0xf
	v_mov_b32_dpp v94, v94 row_ror:2 row_mask:0xf bank_mask:0xf
	v_mov_b32_dpp v69, v75 row_shr:1 row_mask:0xf bank_mask:0xf
	v_mov_b32_dpp v95, v95 row_ror:2 row_mask:0xf bank_mask:0xf
	v_pk_add_f32 v[86:87], v[88:89], 1.0 op_sel_hi:[1,0]
	v_pk_add_f32 v[88:89], v[96:97], 1.0 op_sel_hi:[1,0]
	v_pk_fma_f32 v[90:91], v[74:75], v[22:23], v[26:27]
	v_pk_fma_f32 v[96:97], v[72:73], v[20:21], v[24:25]
	v_mov_b32_dpp v92, v72 row_shr:2 row_mask:0xf bank_mask:0xf
	v_mov_b32_dpp v93, v73 row_shr:2 row_mask:0xf bank_mask:0xf
	v_mov_b32_dpp v94, v74 row_shr:2 row_mask:0xf bank_mask:0xf
	v_mov_b32_dpp v95, v75 row_shr:2 row_mask:0xf bank_mask:0xf
	v_pk_fma_f32 v[68:69], v[18:19], v[68:69], v[90:91]
	v_pk_fma_f32 v[66:67], v[16:17], v[66:67], v[96:97]
	v_pk_fma_f32 v[68:69], v[14:15], v[94:95], v[68:69]
	v_pk_fma_f32 v[66:67], v[12:13], v[92:93], v[66:67]
	v_pk_mul_f32 v[90:91], v[68:69], v[68:69]
	v_pk_mul_f32 v[92:93], v[66:67], v[66:67]
	v_pk_fma_f32 v[90:91], v[90:91], s[30:31], 1.0 op_sel_hi:[1,0,0]
	v_pk_fma_f32 v[92:93], v[92:93], s[30:31], 1.0 op_sel_hi:[1,0,0]
	v_pk_mul_f32 v[90:91], v[68:69], v[90:91]
	v_pk_mul_f32 v[92:93], v[66:67], v[92:93]
	v_pk_mul_f32 v[90:91], v[90:91], s[34:35] op_sel_hi:[1,0]
	v_pk_mul_f32 v[92:93], v[92:93], s[34:35] op_sel_hi:[1,0]
	v_rcp_f32_e32 v88, v88
	v_rcp_f32_e32 v89, v89
	v_rcp_f32_e32 v86, v86
	v_rcp_f32_e32 v87, v87
	v_exp_f32_e32 v92, v92
	v_exp_f32_e32 v90, v90
	v_exp_f32_e32 v91, v91
	v_exp_f32_e32 v93, v93
	v_pk_mul_f32 v[84:85], v[84:85], v[86:87]
	v_pk_mul_f32 v[70:71], v[70:71], v[88:89]
	v_pk_add_f32 v[86:87], v[90:91], 1.0 op_sel_hi:[1,0]
	v_pk_add_f32 v[88:89], v[92:93], 1.0 op_sel_hi:[1,0]
	v_rcp_f32_e32 v86, v86
	v_rcp_f32_e32 v88, v88
	v_rcp_f32_e32 v87, v87
	v_rcp_f32_e32 v89, v89
	v_pk_mul_f32 v[68:69], v[80:81], v[68:69]
	v_pk_mul_f32 v[66:67], v[82:83], v[66:67]
	v_pk_mul_f32 v[68:69], v[68:69], v[86:87]
	v_pk_mul_f32 v[66:67], v[66:67], v[88:89]
	v_mov_b32_e32 v80, v78
	v_cvt_pk_bf16_f32 v66, v66, v67
	v_cvt_pk_bf16_f32 v67, v68, v69
	v_cvt_pk_bf16_f32 v68, v70, v71
	v_mov_b32_e32 v70, v76
	v_mov_b32_e32 v71, v77
	v_mov_b32_e32 v81, v79
	v_mov_b32_dpp v70, v70 row_ror:1 row_mask:0xf bank_mask:0xf
	v_mov_b32_dpp v71, v71 row_ror:1 row_mask:0xf bank_mask:0xf
	v_mov_b32_dpp v80, v80 row_ror:1 row_mask:0xf bank_mask:0xf
	v_mov_b32_dpp v81, v81 row_ror:1 row_mask:0xf bank_mask:0xf
	v_cvt_pk_bf16_f32 v69, v84, v85
	v_mov_b32_dpp v70, v60 row_shr:1 row_mask:0xf bank_mask:0xf
	v_mov_b32_dpp v76, v76 row_ror:2 row_mask:0xf bank_mask:0xf
	v_mov_b32_dpp v71, v61 row_shr:1 row_mask:0xf bank_mask:0xf
	v_mov_b32_dpp v77, v77 row_ror:2 row_mask:0xf bank_mask:0xf
	v_mov_b32_dpp v80, v62 row_shr:1 row_mask:0xf bank_mask:0xf
	v_mov_b32_dpp v78, v78 row_ror:2 row_mask:0xf bank_mask:0xf
	v_mov_b32_dpp v81, v63 row_shr:1 row_mask:0xf bank_mask:0xf
	v_mov_b32_dpp v79, v79 row_ror:2 row_mask:0xf bank_mask:0xf
	v_pk_fma_f32 v[82:83], v[62:63], v[38:39], v[42:43]
	v_pk_fma_f32 v[84:85], v[60:61], v[36:37], v[40:41]
	v_mov_b32_dpp v76, v60 row_shr:2 row_mask:0xf bank_mask:0xf
	v_mov_b32_dpp v77, v61 row_shr:2 row_mask:0xf bank_mask:0xf
	v_mov_b32_dpp v78, v62 row_shr:2 row_mask:0xf bank_mask:0xf
	v_mov_b32_dpp v79, v63 row_shr:2 row_mask:0xf bank_mask:0xf
	v_pk_fma_f32 v[80:81], v[34:35], v[80:81], v[82:83]
	v_pk_fma_f32 v[70:71], v[32:33], v[70:71], v[84:85]
	v_pk_fma_f32 v[78:79], v[30:31], v[78:79], v[80:81]
	v_pk_fma_f32 v[70:71], v[28:29], v[76:77], v[70:71]
	v_pk_mul_f32 v[76:77], v[78:79], v[78:79]
	v_pk_mul_f32 v[80:81], v[70:71], v[70:71]
	v_pk_fma_f32 v[76:77], v[76:77], s[30:31], 1.0 op_sel_hi:[1,0,0]
	v_pk_fma_f32 v[80:81], v[80:81], s[30:31], 1.0 op_sel_hi:[1,0,0]
	v_pk_mul_f32 v[76:77], v[78:79], v[76:77]
	v_pk_mul_f32 v[80:81], v[70:71], v[80:81]
	v_pk_mul_f32 v[76:77], v[76:77], s[34:35] op_sel_hi:[1,0]
	v_pk_mul_f32 v[80:81], v[80:81], s[34:35] op_sel_hi:[1,0]
	v_exp_f32_e32 v76, v76
	v_exp_f32_e32 v80, v80
	v_exp_f32_e32 v77, v77
	v_exp_f32_e32 v81, v81
	v_add_u32_e32 v65, 0xc6000, v64
	global_store_dwordx4 v65, v[66:69], s[18:19] sc1
	v_pk_mul_f32 v[50:51], v[50:51], v[186:187] op_sel_hi:[1,0]
	v_pk_mul_f32 v[48:49], v[48:49], v[186:187] op_sel_hi:[1,0]
	v_mov_b32_e32 v66, v72
	v_mov_b32_e32 v67, v73
	v_mov_b32_e32 v68, v74
	v_mov_b32_e32 v69, v75
	v_mov_b32_dpp v66, v66 row_ror:1 row_mask:0xf bank_mask:0xf
	v_mov_b32_dpp v67, v67 row_ror:1 row_mask:0xf bank_mask:0xf
	v_mov_b32_dpp v68, v68 row_ror:1 row_mask:0xf bank_mask:0xf
	v_mov_b32_dpp v69, v69 row_ror:1 row_mask:0xf bank_mask:0xf
	v_mov_b32_dpp v66, v56 row_shr:1 row_mask:0xf bank_mask:0xf
	v_mov_b32_dpp v72, v72 row_ror:2 row_mask:0xf bank_mask:0xf
	v_mov_b32_dpp v67, v57 row_shr:1 row_mask:0xf bank_mask:0xf
	v_mov_b32_dpp v73, v73 row_ror:2 row_mask:0xf bank_mask:0xf
	v_mov_b32_dpp v68, v58 row_shr:1 row_mask:0xf bank_mask:0xf
	v_mov_b32_dpp v74, v74 row_ror:2 row_mask:0xf bank_mask:0xf
	v_mov_b32_dpp v69, v59 row_shr:1 row_mask:0xf bank_mask:0xf
	v_mov_b32_dpp v75, v75 row_ror:2 row_mask:0xf bank_mask:0xf
	v_pk_mul_f32 v[50:51], v[50:51], v[78:79]
	v_pk_mul_f32 v[48:49], v[48:49], v[70:71]
	v_pk_add_f32 v[70:71], v[76:77], 1.0 op_sel_hi:[1,0]
	v_pk_add_f32 v[76:77], v[80:81], 1.0 op_sel_hi:[1,0]
	v_pk_fma_f32 v[78:79], v[58:59], v[22:23], v[26:27]
	v_pk_fma_f32 v[80:81], v[56:57], v[20:21], v[24:25]
	v_mov_b32_dpp v72, v56 row_shr:2 row_mask:0xf bank_mask:0xf
	v_mov_b32_dpp v73, v57 row_shr:2 row_mask:0xf bank_mask:0xf
	v_mov_b32_dpp v74, v58 row_shr:2 row_mask:0xf bank_mask:0xf
	v_mov_b32_dpp v75, v59 row_shr:2 row_mask:0xf bank_mask:0xf
	v_pk_fma_f32 v[68:69], v[18:19], v[68:69], v[78:79]
	v_pk_fma_f32 v[66:67], v[16:17], v[66:67], v[80:81]
	v_pk_fma_f32 v[68:69], v[14:15], v[74:75], v[68:69]
	v_pk_fma_f32 v[66:67], v[12:13], v[72:73], v[66:67]
	v_pk_mul_f32 v[72:73], v[68:69], v[68:69]
	v_pk_mul_f32 v[74:75], v[66:67], v[66:67]
	v_pk_fma_f32 v[72:73], v[72:73], s[30:31], 1.0 op_sel_hi:[1,0,0]
	v_pk_fma_f32 v[74:75], v[74:75], s[30:31], 1.0 op_sel_hi:[1,0,0]
	v_pk_mul_f32 v[72:73], v[68:69], v[72:73]
	v_pk_mul_f32 v[74:75], v[66:67], v[74:75]
	v_pk_mul_f32 v[72:73], v[72:73], s[34:35] op_sel_hi:[1,0]
	v_pk_mul_f32 v[74:75], v[74:75], s[34:35] op_sel_hi:[1,0]
	v_rcp_f32_e32 v76, v76
	v_rcp_f32_e32 v77, v77
	v_rcp_f32_e32 v70, v70
	v_rcp_f32_e32 v71, v71
	v_exp_f32_e32 v74, v74
	v_exp_f32_e32 v72, v72
	v_exp_f32_e32 v73, v73
	v_exp_f32_e32 v75, v75
	v_pk_mul_f32 v[70:71], v[50:51], v[70:71]
	v_pk_mul_f32 v[50:51], v[48:49], v[76:77]
	v_pk_add_f32 v[48:49], v[72:73], 1.0 op_sel_hi:[1,0]
	v_pk_add_f32 v[72:73], v[74:75], 1.0 op_sel_hi:[1,0]
	v_rcp_f32_e32 v48, v48
	v_rcp_f32_e32 v72, v72
	v_rcp_f32_e32 v49, v49
	v_rcp_f32_e32 v73, v73
	v_pk_mul_f32 v[54:55], v[54:55], v[186:187] op_sel_hi:[1,0]
	v_pk_mul_f32 v[52:53], v[52:53], v[186:187] op_sel_hi:[1,0]
	v_pk_mul_f32 v[54:55], v[54:55], v[68:69]
	v_pk_mul_f32 v[52:53], v[52:53], v[66:67]
	v_pk_mul_f32 v[54:55], v[54:55], v[48:49]
	v_pk_mul_f32 v[48:49], v[52:53], v[72:73]
	v_add_u32_e32 v52, 0xdc000, v64
	v_cvt_pk_bf16_f32 v48, v48, v49
	v_cvt_pk_bf16_f32 v49, v54, v55
	v_cvt_pk_bf16_f32 v50, v50, v51
	v_cvt_pk_bf16_f32 v51, v70, v71
	global_store_dwordx4 v52, v[48:51], s[18:19] sc1
	v_mov_b32_e32 v52, v60
	v_mov_b32_e32 v53, v61
	v_mov_b32_e32 v54, v62
	v_mov_b32_e32 v55, v63
	v_mov_b32_dpp v52, v52 row_ror:1 row_mask:0xf bank_mask:0xf
	v_mov_b32_dpp v60, v60 row_ror:2 row_mask:0xf bank_mask:0xf
	v_mov_b32_dpp v53, v53 row_ror:1 row_mask:0xf bank_mask:0xf
	v_mov_b32_dpp v61, v61 row_ror:2 row_mask:0xf bank_mask:0xf
	v_mov_b32_dpp v54, v54 row_ror:1 row_mask:0xf bank_mask:0xf
	v_mov_b32_dpp v62, v62 row_ror:2 row_mask:0xf bank_mask:0xf
	v_mov_b32_dpp v55, v55 row_ror:1 row_mask:0xf bank_mask:0xf
	v_mov_b32_dpp v63, v63 row_ror:2 row_mask:0xf bank_mask:0xf
	v_mov_b32_dpp v52, v8 row_shr:1 row_mask:0xf bank_mask:0xf
	v_mov_b32_dpp v60, v8 row_shr:2 row_mask:0xf bank_mask:0xf
	v_mov_b32_dpp v53, v9 row_shr:1 row_mask:0xf bank_mask:0xf
	v_mov_b32_dpp v61, v9 row_shr:2 row_mask:0xf bank_mask:0xf
	v_mov_b32_dpp v54, v10 row_shr:1 row_mask:0xf bank_mask:0xf
	v_mov_b32_dpp v62, v10 row_shr:2 row_mask:0xf bank_mask:0xf
	v_mov_b32_dpp v55, v11 row_shr:1 row_mask:0xf bank_mask:0xf
	v_mov_b32_dpp v63, v11 row_shr:2 row_mask:0xf bank_mask:0xf
	v_pk_fma_f32 v[10:11], v[10:11], v[38:39], v[42:43]
	v_pk_fma_f32 v[8:9], v[8:9], v[36:37], v[40:41]
	v_pk_fma_f32 v[10:11], v[34:35], v[54:55], v[10:11]
	v_pk_fma_f32 v[8:9], v[32:33], v[52:53], v[8:9]
	v_pk_fma_f32 v[10:11], v[30:31], v[62:63], v[10:11]
	v_pk_fma_f32 v[8:9], v[28:29], v[60:61], v[8:9]
	v_mov_b32_e32 v48, v56
	v_mov_b32_e32 v49, v57
	v_mov_b32_e32 v50, v58
	v_mov_b32_e32 v51, v59
	v_pk_mul_f32 v[28:29], v[10:11], v[10:11]
	v_pk_mul_f32 v[30:31], v[8:9], v[8:9]
	v_mov_b32_dpp v48, v48 row_ror:1 row_mask:0xf bank_mask:0xf
	v_mov_b32_dpp v56, v56 row_ror:2 row_mask:0xf bank_mask:0xf
	v_mov_b32_dpp v49, v49 row_ror:1 row_mask:0xf bank_mask:0xf
	v_mov_b32_dpp v57, v57 row_ror:2 row_mask:0xf bank_mask:0xf
	v_mov_b32_dpp v50, v50 row_ror:1 row_mask:0xf bank_mask:0xf
	v_mov_b32_dpp v58, v58 row_ror:2 row_mask:0xf bank_mask:0xf
	v_mov_b32_dpp v51, v51 row_ror:1 row_mask:0xf bank_mask:0xf
	v_mov_b32_dpp v59, v59 row_ror:2 row_mask:0xf bank_mask:0xf
	v_pk_fma_f32 v[28:29], v[28:29], s[30:31], 1.0 op_sel_hi:[1,0,0]
	v_pk_fma_f32 v[30:31], v[30:31], s[30:31], 1.0 op_sel_hi:[1,0,0]
	v_mov_b32_dpp v48, v4 row_shr:1 row_mask:0xf bank_mask:0xf
	v_mov_b32_dpp v56, v4 row_shr:2 row_mask:0xf bank_mask:0xf
	v_mov_b32_dpp v49, v5 row_shr:1 row_mask:0xf bank_mask:0xf
	v_mov_b32_dpp v57, v5 row_shr:2 row_mask:0xf bank_mask:0xf
	v_mov_b32_dpp v50, v6 row_shr:1 row_mask:0xf bank_mask:0xf
	v_mov_b32_dpp v58, v6 row_shr:2 row_mask:0xf bank_mask:0xf
	v_mov_b32_dpp v51, v7 row_shr:1 row_mask:0xf bank_mask:0xf
	v_mov_b32_dpp v59, v7 row_shr:2 row_mask:0xf bank_mask:0xf
	v_pk_mul_f32 v[28:29], v[10:11], v[28:29]
	v_pk_mul_f32 v[30:31], v[8:9], v[30:31]
	v_pk_fma_f32 v[6:7], v[6:7], v[22:23], v[26:27]
	v_pk_fma_f32 v[4:5], v[4:5], v[20:21], v[24:25]
	v_pk_mul_f32 v[28:29], v[28:29], s[34:35] op_sel_hi:[1,0]
	v_pk_mul_f32 v[30:31], v[30:31], s[34:35] op_sel_hi:[1,0]
	v_pk_fma_f32 v[6:7], v[18:19], v[50:51], v[6:7]
	v_pk_fma_f32 v[4:5], v[16:17], v[48:49], v[4:5]
	v_exp_f32_e32 v30, v30
	v_exp_f32_e32 v28, v28
	v_exp_f32_e32 v29, v29
	v_exp_f32_e32 v31, v31
	v_pk_fma_f32 v[6:7], v[14:15], v[58:59], v[6:7]
	v_pk_fma_f32 v[4:5], v[12:13], v[56:57], v[4:5]
	v_pk_mul_f32 v[12:13], v[6:7], v[6:7]
	v_pk_mul_f32 v[14:15], v[4:5], v[4:5]
	v_mov_b32_e32 v183, v182
	v_pk_fma_f32 v[12:13], v[12:13], s[30:31], 1.0 op_sel_hi:[1,0,0]
	v_pk_fma_f32 v[14:15], v[14:15], s[30:31], 1.0 op_sel_hi:[1,0,0]
	v_pk_mul_f32 v[0:1], v[0:1], v[182:183]
	v_pk_mul_f32 v[12:13], v[6:7], v[12:13]
	v_pk_mul_f32 v[14:15], v[4:5], v[14:15]
	v_pk_mul_f32 v[2:3], v[2:3], v[10:11]
	v_pk_mul_f32 v[0:1], v[0:1], v[8:9]
	v_pk_add_f32 v[8:9], v[28:29], 1.0 op_sel_hi:[1,0]
	v_pk_add_f32 v[10:11], v[30:31], 1.0 op_sel_hi:[1,0]
	v_pk_mul_f32 v[12:13], v[12:13], s[34:35] op_sel_hi:[1,0]
	v_pk_mul_f32 v[14:15], v[14:15], s[34:35] op_sel_hi:[1,0]
	v_rcp_f32_e32 v10, v10
	v_rcp_f32_e32 v11, v11
	v_rcp_f32_e32 v8, v8
	v_rcp_f32_e32 v9, v9
	v_exp_f32_e32 v14, v14
	v_exp_f32_e32 v12, v12
	v_exp_f32_e32 v13, v13
	v_exp_f32_e32 v15, v15
	v_pk_mul_f32 v[8:9], v[2:3], v[8:9]
	v_pk_mul_f32 v[2:3], v[0:1], v[10:11]
	v_pk_add_f32 v[0:1], v[12:13], 1.0 op_sel_hi:[1,0]
	v_pk_add_f32 v[10:11], v[14:15], 1.0 op_sel_hi:[1,0]
	v_rcp_f32_e32 v0, v0
	v_rcp_f32_e32 v10, v10
	v_rcp_f32_e32 v1, v1
	v_rcp_f32_e32 v11, v11
	v_pk_mul_f32 v[44:45], v[44:45], v[182:183]
	v_pk_mul_f32 v[6:7], v[46:47], v[6:7]
	v_pk_mul_f32 v[4:5], v[44:45], v[4:5]
	v_pk_mul_f32 v[6:7], v[6:7], v[0:1]
	v_pk_mul_f32 v[0:1], v[4:5], v[10:11]
	v_add_u32_e32 v4, 0xf2000, v64
	s_cmp_eq_u32 s65, s76
	s_mov_b64 s[54:55], -1
	v_cvt_pk_bf16_f32 v0, v0, v1
	v_cvt_pk_bf16_f32 v1, v6, v7
	v_cvt_pk_bf16_f32 v2, v2, v3
	v_cvt_pk_bf16_f32 v3, v8, v9
	global_store_dwordx4 v4, v[0:3], s[18:19] sc1
	s_cbranch_scc1 .LBB0_1250
	s_and_b64 vcc, exec, s[4:5]
	s_cbranch_vccnz .LBB0_1249
	s_barrier
	s_branch .LBB0_1249
